# grid barrier: non-leader blocks poll TOPGEN directly, drop per-XCD XGEN relay
# speedup vs baseline: 1.0234x; 1.0234x over previous
.LBB0_75:
	s_or_b64 exec, exec, s[12:13]
	v_cvt_f32_u32_e32 v4, v2
	s_waitcnt vmcnt(0)
	v_readfirstlane_b32 s3, v3
	v_sub_u32_e32 v3, 0, v2
	v_rcp_iflag_f32_e32 v4, v4
	v_add_u32_e32 v5, s3, v1
	v_mul_f32_e32 v4, 0x4f7ffffe, v4
	v_cvt_u32_f32_e32 v4, v4
	v_mul_lo_u32 v1, v3, v4
	v_mul_hi_u32 v1, v4, v1
	v_add_u32_e32 v1, v4, v1
	v_mul_hi_u32 v1, v5, v1
	v_mul_lo_u32 v3, v1, v2
	v_sub_u32_e32 v3, v5, v3
	v_add_u32_e32 v4, 1, v1
	v_cmp_ge_u32_e32 vcc, v3, v2
	s_nop 1
	v_cndmask_b32_e32 v1, v1, v4, vcc
	v_sub_u32_e32 v4, v3, v2
	v_cndmask_b32_e32 v3, v3, v4, vcc
	v_add_u32_e32 v4, 1, v1
	v_cmp_ge_u32_e32 vcc, v3, v2
	v_add_u32_e32 v3, 1, v5
	s_nop 0
	v_cndmask_b32_e32 v1, v1, v4, vcc
	v_mul_lo_u32 v4, v2, v1
	v_add_u32_e32 v2, v4, v2
	v_cmp_ne_u32_e32 vcc, v3, v2
	s_and_saveexec_b64 s[10:11], vcc
	s_xor_b64 s[10:11], exec, s[10:11]
	s_cbranch_execz .LBB0_89
	s_waitcnt lgkmcnt(0)
	v_mov_b32_e32 v0, 0
	s_add_u32 s16, s34, 0x3e03500
	s_addc_u32 s17, s35, 0
	global_load_dword v0, v0, s[16:17] sc1
	s_waitcnt vmcnt(0)
	v_cmp_eq_u32_e32 vcc, v0, v1
	s_and_saveexec_b64 s[12:13], vcc
	s_cbranch_execz .LBB0_88
	s_add_u32 s14, s34, 0x3e00200
	s_addc_u32 s15, s35, 0
	s_mov_b32 s3, 1
	s_mov_b64 s[18:19], 0
	v_mov_b32_e32 v0, 0
	s_branch .LBB0_79

.LBB0_106:
	s_or_b64 exec, exec, s[10:11]
	s_mov_b64 s[10:11], exec
	v_mbcnt_lo_u32_b32 v0, s10, 0
	v_mbcnt_hi_u32_b32 v0, s11, v0
	v_cmp_eq_u32_e32 vcc, 0, v0
	s_waitcnt vmcnt(0)
	buffer_inv sc1
	s_and_saveexec_b64 s[12:13], vcc
	s_cbranch_execz .LBB0_108
	s_bcnt1_i32_b64 s3, s[10:11]
	v_mov_b32_e32 v0, 0x2000
	v_mov_b32_e32 v1, s3
.LBB0_108:
	s_or_b64 exec, exec, s[12:13]
	s_waitcnt vmcnt(0)

.LBB0_183:
	s_or_b64 exec, exec, s[10:11]
	s_mov_b64 s[10:11], exec
	v_mbcnt_lo_u32_b32 v0, s10, 0
	v_mbcnt_hi_u32_b32 v0, s11, v0
	v_cmp_eq_u32_e32 vcc, 0, v0
	s_waitcnt vmcnt(0)
	buffer_inv sc1
	s_and_saveexec_b64 s[12:13], vcc
	s_cbranch_execz .LBB0_185
	s_bcnt1_i32_b64 s3, s[10:11]
	v_mov_b32_e32 v0, 0x2000
	v_mov_b32_e32 v1, s3
.LBB0_185:
	s_or_b64 exec, exec, s[12:13]
	s_waitcnt vmcnt(0)

.LBB0_255:
	s_or_b64 exec, exec, s[10:11]
	s_mov_b64 s[10:11], exec
	v_mbcnt_lo_u32_b32 v0, s10, 0
	v_mbcnt_hi_u32_b32 v0, s11, v0
	v_cmp_eq_u32_e32 vcc, 0, v0
	s_waitcnt vmcnt(0)
	buffer_inv sc1
	s_and_saveexec_b64 s[12:13], vcc
	s_cbranch_execz .LBB0_257
	s_bcnt1_i32_b64 s3, s[10:11]
	v_mov_b32_e32 v0, 0x2000
	v_mov_b32_e32 v1, s3
.LBB0_257:
	s_or_b64 exec, exec, s[12:13]
	s_waitcnt vmcnt(0)

.LBB0_319:
	s_or_b64 exec, exec, s[10:11]
	s_mov_b64 s[10:11], exec
	v_mbcnt_lo_u32_b32 v0, s10, 0
	v_mbcnt_hi_u32_b32 v0, s11, v0
	v_cmp_eq_u32_e32 vcc, 0, v0
	s_waitcnt vmcnt(0)
	buffer_inv sc1
	s_and_saveexec_b64 s[12:13], vcc
	s_cbranch_execz .LBB0_321
	s_bcnt1_i32_b64 s3, s[10:11]
	v_mov_b32_e32 v0, 0x2000
	v_mov_b32_e32 v1, s3
.LBB0_321:
	s_or_b64 exec, exec, s[12:13]
	s_waitcnt vmcnt(0)

.LBB0_445:
	s_or_b64 exec, exec, s[10:11]
	s_mov_b64 s[10:11], exec
	v_mbcnt_lo_u32_b32 v0, s10, 0
	v_mbcnt_hi_u32_b32 v0, s11, v0
	v_cmp_eq_u32_e32 vcc, 0, v0
	s_waitcnt vmcnt(0)
	buffer_inv sc1
	s_and_saveexec_b64 s[12:13], vcc
	s_cbranch_execz .LBB0_447
	s_bcnt1_i32_b64 s3, s[10:11]
	v_mov_b32_e32 v0, 0x2000
	v_mov_b32_e32 v1, s3
.LBB0_447:
	s_or_b64 exec, exec, s[12:13]
	s_waitcnt vmcnt(0)

.LBB0_511:
	s_or_b64 exec, exec, s[10:11]
	s_mov_b64 s[10:11], exec
	v_mbcnt_lo_u32_b32 v0, s10, 0
	v_mbcnt_hi_u32_b32 v0, s11, v0
	v_cmp_eq_u32_e32 vcc, 0, v0
	s_waitcnt vmcnt(0)
	buffer_inv sc1
	s_and_saveexec_b64 s[12:13], vcc
	s_cbranch_execz .LBB0_513
	s_bcnt1_i32_b64 s3, s[10:11]
	v_mov_b32_e32 v0, 0x2000
	v_mov_b32_e32 v1, s3
.LBB0_513:
	s_or_b64 exec, exec, s[12:13]
	s_waitcnt vmcnt(0)

.LBB0_558:
	s_or_b64 exec, exec, s[10:11]
	v_cvt_f32_u32_e32 v4, v2
	s_waitcnt vmcnt(0)
	v_readfirstlane_b32 s3, v3
	v_sub_u32_e32 v3, 0, v2
	v_rcp_iflag_f32_e32 v4, v4
	v_add_u32_e32 v5, s3, v1
	v_mul_f32_e32 v4, 0x4f7ffffe, v4
	v_cvt_u32_f32_e32 v4, v4
	v_mul_lo_u32 v1, v3, v4
	v_mul_hi_u32 v1, v4, v1
	v_add_u32_e32 v1, v4, v1
	v_mul_hi_u32 v1, v5, v1
	v_mul_lo_u32 v3, v1, v2
	v_sub_u32_e32 v3, v5, v3
	v_add_u32_e32 v4, 1, v1
	v_cmp_ge_u32_e32 vcc, v3, v2
	s_nop 1
	v_cndmask_b32_e32 v1, v1, v4, vcc
	v_sub_u32_e32 v4, v3, v2
	v_cndmask_b32_e32 v3, v3, v4, vcc
	v_add_u32_e32 v4, 1, v1
	v_cmp_ge_u32_e32 vcc, v3, v2
	v_add_u32_e32 v3, 1, v5
	s_nop 0
	v_cndmask_b32_e32 v1, v1, v4, vcc
	v_mul_lo_u32 v4, v2, v1
	v_add_u32_e32 v2, v4, v2
	v_cmp_ne_u32_e32 vcc, v3, v2
	s_and_saveexec_b64 s[8:9], vcc
	s_xor_b64 s[8:9], exec, s[8:9]
	s_cbranch_execz .LBB0_572
	s_waitcnt lgkmcnt(0)
	v_mov_b32_e32 v0, 0
	s_add_u32 s14, s34, 0x3e03500
	s_addc_u32 s15, s35, 0
	global_load_dword v0, v0, s[14:15] sc1
	s_waitcnt vmcnt(0)
	v_cmp_eq_u32_e32 vcc, v0, v1
	s_and_saveexec_b64 s[10:11], vcc
	s_cbranch_execz .LBB0_571
	s_add_u32 s12, s34, 0x3e00200
	s_addc_u32 s13, s35, 0
	s_mov_b32 s3, 1
	s_mov_b64 s[16:17], 0
	v_mov_b32_e32 v0, 0
	s_branch .LBB0_562

.LBB0_589:
	s_or_b64 exec, exec, s[8:9]
	s_mov_b64 s[8:9], exec
	v_mbcnt_lo_u32_b32 v0, s8, 0
	v_mbcnt_hi_u32_b32 v0, s9, v0
	v_cmp_eq_u32_e32 vcc, 0, v0
	s_waitcnt vmcnt(0)
	buffer_inv sc1
	s_and_saveexec_b64 s[10:11], vcc
	s_cbranch_execz .LBB0_591
	s_bcnt1_i32_b64 s3, s[8:9]
	v_mov_b32_e32 v0, 0x2000
	v_mov_b32_e32 v1, s3
.LBB0_591:
	s_or_b64 exec, exec, s[10:11]
	s_waitcnt vmcnt(0)

.LBB0_653:
	s_or_b64 exec, exec, s[8:9]
	s_mov_b64 s[8:9], exec
	v_mbcnt_lo_u32_b32 v0, s8, 0
	v_mbcnt_hi_u32_b32 v0, s9, v0
	v_cmp_eq_u32_e32 vcc, 0, v0
	s_waitcnt vmcnt(0)
	buffer_inv sc1
	s_and_saveexec_b64 s[10:11], vcc
	s_cbranch_execz .LBB0_655
	s_bcnt1_i32_b64 s3, s[8:9]
	v_mov_b32_e32 v0, 0x2000
	v_mov_b32_e32 v1, s3
.LBB0_655:
	s_or_b64 exec, exec, s[10:11]
	s_waitcnt vmcnt(0)

.LBB0_738:
	s_or_b64 exec, exec, s[10:11]
	s_mov_b64 s[10:11], exec
	v_mbcnt_lo_u32_b32 v0, s10, 0
	v_mbcnt_hi_u32_b32 v0, s11, v0
	v_cmp_eq_u32_e32 vcc, 0, v0
	s_waitcnt vmcnt(0)
	buffer_inv sc1
	s_and_saveexec_b64 s[12:13], vcc
	s_cbranch_execz .LBB0_740
	s_bcnt1_i32_b64 s3, s[10:11]
	v_mov_b32_e32 v0, 0x2000
	v_mov_b32_e32 v1, s3
.LBB0_740:
	s_or_b64 exec, exec, s[12:13]
	s_waitcnt vmcnt(0)

.LBB0_802:
	s_or_b64 exec, exec, s[10:11]
	s_mov_b64 s[10:11], exec
	v_mbcnt_lo_u32_b32 v0, s10, 0
	v_mbcnt_hi_u32_b32 v0, s11, v0
	v_cmp_eq_u32_e32 vcc, 0, v0
	s_waitcnt vmcnt(0)
	buffer_inv sc1
	s_and_saveexec_b64 s[12:13], vcc
	s_cbranch_execz .LBB0_804
	s_bcnt1_i32_b64 s3, s[10:11]
	v_mov_b32_e32 v0, 0x2000
	v_mov_b32_e32 v1, s3
.LBB0_804:
	s_or_b64 exec, exec, s[12:13]
	s_waitcnt vmcnt(0)

.LBB0_925:
	s_or_b64 exec, exec, s[8:9]
	s_mov_b64 s[8:9], exec
	v_mbcnt_lo_u32_b32 v0, s8, 0
	v_mbcnt_hi_u32_b32 v0, s9, v0
	v_cmp_eq_u32_e32 vcc, 0, v0
	s_waitcnt vmcnt(0)
	buffer_inv sc1
	s_and_saveexec_b64 s[10:11], vcc
	s_cbranch_execz .LBB0_927
	s_bcnt1_i32_b64 s3, s[8:9]
	v_mov_b32_e32 v0, 0x2000
	v_mov_b32_e32 v1, s3
.LBB0_927:
	s_or_b64 exec, exec, s[10:11]
	s_waitcnt vmcnt(0)

.LBB0_1013:
	s_or_b64 exec, exec, s[8:9]
	s_mov_b64 s[8:9], exec
	v_mbcnt_lo_u32_b32 v0, s8, 0
	v_mbcnt_hi_u32_b32 v0, s9, v0
	v_cmp_eq_u32_e32 vcc, 0, v0
	s_waitcnt vmcnt(0)
	buffer_inv sc1
	s_and_saveexec_b64 s[10:11], vcc
	s_cbranch_execz .LBB0_1015
	s_bcnt1_i32_b64 s3, s[8:9]
	v_mov_b32_e32 v0, 0x2000
	v_mov_b32_e32 v1, s3
.LBB0_1015:
	s_or_b64 exec, exec, s[10:11]
	s_waitcnt vmcnt(0)

.LBB0_1251:
	s_or_b64 exec, exec, s[8:9]
	s_mov_b64 s[8:9], exec
	v_mbcnt_lo_u32_b32 v0, s8, 0
	v_mbcnt_hi_u32_b32 v0, s9, v0
	v_cmp_eq_u32_e32 vcc, 0, v0
	s_waitcnt vmcnt(0)
	buffer_inv sc1
	s_and_saveexec_b64 s[10:11], vcc
	s_cbranch_execz .LBB0_1253
	s_bcnt1_i32_b64 s3, s[8:9]
	v_mov_b32_e32 v0, 0x2000
	v_mov_b32_e32 v1, s3
.LBB0_1253:
	s_or_b64 exec, exec, s[10:11]
	s_waitcnt vmcnt(0)

.LBB0_1292:
	s_or_b64 exec, exec, s[8:9]
	v_cvt_f32_u32_e32 v4, v2
	s_waitcnt vmcnt(0)
	v_readfirstlane_b32 s3, v3
	v_sub_u32_e32 v3, 0, v2
	v_rcp_iflag_f32_e32 v4, v4
	v_add_u32_e32 v5, s3, v1
	v_mul_f32_e32 v4, 0x4f7ffffe, v4
	v_cvt_u32_f32_e32 v4, v4
	v_mul_lo_u32 v1, v3, v4
	v_mul_hi_u32 v1, v4, v1
	v_add_u32_e32 v1, v4, v1
	v_mul_hi_u32 v1, v5, v1
	v_mul_lo_u32 v3, v1, v2
	v_sub_u32_e32 v3, v5, v3
	v_add_u32_e32 v4, 1, v1
	v_cmp_ge_u32_e32 vcc, v3, v2
	s_nop 1
	v_cndmask_b32_e32 v1, v1, v4, vcc
	v_sub_u32_e32 v4, v3, v2
	v_cndmask_b32_e32 v3, v3, v4, vcc
	v_add_u32_e32 v4, 1, v1
	v_cmp_ge_u32_e32 vcc, v3, v2
	v_add_u32_e32 v3, 1, v5
	s_nop 0
	v_cndmask_b32_e32 v1, v1, v4, vcc
	v_mul_lo_u32 v4, v2, v1
	v_add_u32_e32 v2, v4, v2
	v_cmp_ne_u32_e32 vcc, v3, v2
	s_and_saveexec_b64 s[6:7], vcc
	s_xor_b64 s[6:7], exec, s[6:7]
	s_cbranch_execz .LBB0_1306
	s_waitcnt lgkmcnt(0)
	v_mov_b32_e32 v0, 0
	s_add_u32 s12, s34, 0x3e03500
	s_addc_u32 s13, s35, 0
	global_load_dword v0, v0, s[12:13] sc1
	s_waitcnt vmcnt(0)
	v_cmp_eq_u32_e32 vcc, v0, v1
	s_and_saveexec_b64 s[8:9], vcc
	s_cbranch_execz .LBB0_1305
	s_add_u32 s10, s34, 0x3e00200
	s_addc_u32 s11, s35, 0
	s_mov_b32 s3, 1
	s_mov_b64 s[14:15], 0
	v_mov_b32_e32 v0, 0
	s_branch .LBB0_1296

.LBB0_1323:
	s_or_b64 exec, exec, s[6:7]
	s_mov_b64 s[6:7], exec
	v_mbcnt_lo_u32_b32 v0, s6, 0
	v_mbcnt_hi_u32_b32 v0, s7, v0
	v_cmp_eq_u32_e32 vcc, 0, v0
	s_waitcnt vmcnt(0)
	buffer_inv sc1
	s_and_saveexec_b64 s[8:9], vcc
	s_cbranch_execz .LBB0_1325
	s_bcnt1_i32_b64 s3, s[6:7]
	v_mov_b32_e32 v0, 0x2000
	v_mov_b32_e32 v1, s3
.LBB0_1325:
	s_or_b64 exec, exec, s[8:9]
	s_waitcnt vmcnt(0)

.LBB0_1387:
	s_or_b64 exec, exec, s[8:9]
	s_mov_b64 s[8:9], exec
	v_mbcnt_lo_u32_b32 v0, s8, 0
	v_mbcnt_hi_u32_b32 v0, s9, v0
	v_cmp_eq_u32_e32 vcc, 0, v0
	s_waitcnt vmcnt(0)
	buffer_inv sc1
	s_and_saveexec_b64 s[10:11], vcc
	s_cbranch_execz .LBB0_1389
	s_bcnt1_i32_b64 s3, s[8:9]
	v_mov_b32_e32 v0, 0x2000
	v_mov_b32_e32 v1, s3
.LBB0_1389:
	s_or_b64 exec, exec, s[10:11]
	s_waitcnt vmcnt(0)

.LBB0_1480:
	s_or_b64 exec, exec, s[8:9]
	s_mov_b64 s[8:9], exec
	v_mbcnt_lo_u32_b32 v0, s8, 0
	v_mbcnt_hi_u32_b32 v0, s9, v0
	v_cmp_eq_u32_e32 vcc, 0, v0
	s_waitcnt vmcnt(0)
	buffer_inv sc1
	s_and_saveexec_b64 s[10:11], vcc
	s_cbranch_execz .LBB0_1482
	s_bcnt1_i32_b64 s3, s[8:9]
	v_mov_b32_e32 v0, 0x2000
	v_mov_b32_e32 v1, s3
.LBB0_1482:
	s_or_b64 exec, exec, s[10:11]
	s_waitcnt vmcnt(0)

.LBB0_1556:
	s_or_b64 exec, exec, s[8:9]
	s_mov_b64 s[8:9], exec
	v_mbcnt_lo_u32_b32 v0, s8, 0
	v_mbcnt_hi_u32_b32 v0, s9, v0
	v_cmp_eq_u32_e32 vcc, 0, v0
	s_waitcnt vmcnt(0)
	buffer_inv sc1
	s_and_saveexec_b64 s[10:11], vcc
	s_cbranch_execz .LBB0_1558
	s_bcnt1_i32_b64 s3, s[8:9]
	v_mov_b32_e32 v0, 0x2000
	v_mov_b32_e32 v1, s3
.LBB0_1558:
	s_or_b64 exec, exec, s[10:11]
	s_waitcnt vmcnt(0)

.LBB0_1628:
	s_or_b64 exec, exec, s[8:9]
	s_mov_b64 s[8:9], exec
	v_mbcnt_lo_u32_b32 v0, s8, 0
	v_mbcnt_hi_u32_b32 v0, s9, v0
	v_cmp_eq_u32_e32 vcc, 0, v0
	s_waitcnt vmcnt(0)
	buffer_inv sc1
	s_and_saveexec_b64 s[10:11], vcc
	s_cbranch_execz .LBB0_1630
	s_bcnt1_i32_b64 s3, s[8:9]
	v_mov_b32_e32 v0, 0x2000
	v_mov_b32_e32 v1, s3
.LBB0_1630:
	s_or_b64 exec, exec, s[10:11]
	s_waitcnt vmcnt(0)

.LBB0_1692:
	s_or_b64 exec, exec, s[8:9]
	s_mov_b64 s[8:9], exec
	v_mbcnt_lo_u32_b32 v0, s8, 0
	v_mbcnt_hi_u32_b32 v0, s9, v0
	v_cmp_eq_u32_e32 vcc, 0, v0
	s_waitcnt vmcnt(0)
	buffer_inv sc1
	s_and_saveexec_b64 s[10:11], vcc
	s_cbranch_execz .LBB0_1694
	s_bcnt1_i32_b64 s3, s[8:9]
	v_mov_b32_e32 v0, 0x2000
	v_mov_b32_e32 v1, s3
.LBB0_1694:
	s_or_b64 exec, exec, s[10:11]
	s_waitcnt vmcnt(0)

.LBB0_1726:
	s_or_b64 exec, exec, s[6:7]
	v_cvt_f32_u32_e32 v4, v2
	s_waitcnt vmcnt(0)
	v_readfirstlane_b32 s4, v3
	v_sub_u32_e32 v3, 0, v2
	v_rcp_iflag_f32_e32 v4, v4
	v_add_u32_e32 v5, s4, v1
	v_mul_f32_e32 v4, 0x4f7ffffe, v4
	v_cvt_u32_f32_e32 v4, v4
	v_mul_lo_u32 v1, v3, v4
	v_mul_hi_u32 v1, v4, v1
	v_add_u32_e32 v1, v4, v1
	v_mul_hi_u32 v1, v5, v1
	v_mul_lo_u32 v3, v1, v2
	v_sub_u32_e32 v3, v5, v3
	v_add_u32_e32 v4, 1, v1
	v_cmp_ge_u32_e32 vcc, v3, v2
	s_nop 1
	v_cndmask_b32_e32 v1, v1, v4, vcc
	v_sub_u32_e32 v4, v3, v2
	v_cndmask_b32_e32 v3, v3, v4, vcc
	v_add_u32_e32 v4, 1, v1
	v_cmp_ge_u32_e32 vcc, v3, v2
	v_add_u32_e32 v3, 1, v5
	s_nop 0
	v_cndmask_b32_e32 v1, v1, v4, vcc
	v_mul_lo_u32 v4, v2, v1
	v_add_u32_e32 v2, v4, v2
	v_cmp_ne_u32_e32 vcc, v3, v2
	s_and_saveexec_b64 s[4:5], vcc
	s_xor_b64 s[4:5], exec, s[4:5]
	s_cbranch_execz .LBB0_1740
	s_waitcnt lgkmcnt(0)
	v_mov_b32_e32 v0, 0
	s_add_u32 s10, s34, 0x3e03500
	s_addc_u32 s11, s35, 0
	global_load_dword v0, v0, s[10:11] sc1
	s_waitcnt vmcnt(0)
	v_cmp_eq_u32_e32 vcc, v0, v1
	s_and_saveexec_b64 s[6:7], vcc
	s_cbranch_execz .LBB0_1739
	s_add_u32 s8, s34, 0x3e00200
	s_addc_u32 s9, s35, 0
	s_mov_b32 s22, 1
	s_mov_b64 s[12:13], 0
	v_mov_b32_e32 v0, 0
	s_branch .LBB0_1730

.LBB0_1757:
	s_or_b64 exec, exec, s[4:5]
	s_mov_b64 s[4:5], exec
	v_mbcnt_lo_u32_b32 v0, s4, 0
	v_mbcnt_hi_u32_b32 v0, s5, v0
	v_cmp_eq_u32_e32 vcc, 0, v0
	s_waitcnt vmcnt(0)
	buffer_inv sc1
	s_and_saveexec_b64 s[6:7], vcc
	s_cbranch_execz .LBB0_1759
	s_bcnt1_i32_b64 s4, s[4:5]
	v_mov_b32_e32 v0, 0x2000
	v_mov_b32_e32 v1, s4
.LBB0_1759:
	s_or_b64 exec, exec, s[6:7]
	s_waitcnt vmcnt(0)
